# conv h=1: third (half-occupied) round split into two 8-token half-items so all workgroups take part; plus earlier post/final-norm edits
# speedup vs baseline: 1.0130x; 1.0034x over previous
; __device__ void conv_phase(int swave, const Params& p, int layer, int h) {
;     ...
;   for (int it = bidx * 512 + tidx; it < (TOK / 16) * NG; it += gridDim.x * 512) {
.LBB0_707:
	v_add_u32_e32 v135, s57, v135
	s_cmpk_lg_u32 s34, 0x500
	s_cbranch_scc1 .Lconv_std
	s_cmp_lg_u32 s57, 0x20000
	s_cbranch_scc1 .Lconv_std
	s_mov_b32 s2, 0x40000
	v_cmp_le_i32_e32 vcc, s2, v135
	s_cbranch_vccnz .Lconv_half
.Lconv_std:
	v_cmp_le_i32_e32 vcc, s44, v135
	s_or_b64 s[12:13], vcc, s[12:13]
	s_andn2_b64 exec, exec, s[12:13]
	s_cbranch_execz .LBB0_715

; __device__ __forceinline__ float lo_bf(unsigned u) { return __uint_as_float(u << 16); }
; __device__ void conv_phase(int swave, const Params& p, int layer, int h) {
;     ...
;     const int f8 = (it % NG) * 8, t0 = (it / NG) * 16, s0 = t0 & (SEQ - 1);
;     const int fa = FC0 + f8, fv = FFN + FC0 + f8;
;     float wa[3][8], wv[3][8], ba[8], bv[8];
; #pragma unroll
;     for (int tap = 0; tap < 3; ++tap) {
;       const float4 a0 = *(const float4*)(cw + tap * 5632 + fa), a1 = *(const float4*)(cw + tap * 5632 + fa + 4);
;       const float4 v0 = *(const float4*)(cw + tap * 5632 + fv), v1 = *(const float4*)(cw + tap * 5632 + fv + 4);
;       wa[tap][0] = a0.x; wa[tap][1] = a0.y; wa[tap][2] = a0.z; wa[tap][3] = a0.w; wa[tap][4] = a1.x; wa[tap][5] = a1.y; wa[tap][6] = a1.z; wa[tap][7] = a1.w;
;       wv[tap][0] = v0.x; wv[tap][1] = v0.y; wv[tap][2] = v0.z; wv[tap][3] = v0.w; wv[tap][4] = v1.x; wv[tap][5] = v1.y; wv[tap][6] = v1.z; wv[tap][7] = v1.w;
;     }
;     {
;       const float4 a0 = *(const float4*)(cb + fa), a1 = *(const float4*)(cb + fa + 4), v0 = *(const float4*)(cb + fv), v1 = *(const float4*)(cb + fv + 4);
;       ba[0] = a0.x; ba[1] = a0.y; ba[2] = a0.z; ba[3] = a0.w; ba[4] = a1.x; ba[5] = a1.y; ba[6] = a1.z; ba[7] = a1.w;
;       bv[0] = v0.x; bv[1] = v0.y; bv[2] = v0.z; bv[3] = v0.w; bv[4] = v1.x; bv[5] = v1.y; bv[6] = v1.z; bv[7] = v1.w;
;     }
;     const bf16_t* base = U + (size_t)t0 * ULD + f8;
;     const uint4 zero4 = make_uint4(0u, 0u, 0u, 0u);
;     uint4 pa = zero4, pv = zero4;
;     if (s0 > 0) { pa = ld_nt16(base - ULD); pv = ld_nt16(base - ULD + FFNH); }
;     uint4 ca = ld_nt16(base), cv = ld_nt16(base + FFNH);
; #pragma unroll 4
;     for (int i = 0; i < 16; ++i) {
;       uint4 na = zero4, nv = zero4;
;       if (s0 + i + 1 < SEQ) { na = ld_nt16(base + (size_t)(i + 1) * ULD); nv = ld_nt16(base + (size_t)(i + 1) * ULD + FFNH); }
;       const unsigned rp[4] = {pa.x, pa.y, pa.z, pa.w}, rc[4] = {ca.x, ca.y, ca.z, ca.w}, rn[4] = {na.x, na.y, na.z, na.w};
;       const unsigned qp[4] = {pv.x, pv.y, pv.z, pv.w}, qc[4] = {cv.x, cv.y, cv.z, cv.w}, qn[4] = {nv.x, nv.y, nv.z, nv.w};
;       float oa[8], ov[8];
; #pragma unroll
;       for (int e = 0; e < 4; ++e) {
;         oa[2 * e] = ba[2 * e] + lo_bf(rp[e]) * wa[0][2 * e] + lo_bf(rc[e]) * wa[1][2 * e] + lo_bf(rn[e]) * wa[2][2 * e];
.Lconv_half:
	v_subrev_u32_e32 v143, s2, v135
	v_lshrrev_b32_e32 v144, 16, v143
	v_and_b32_e32 v143, 0xffff, v143
	v_add_u32_e32 v143, s2, v143
	v_mul_hi_u32 v0, v143, v142
	v_mul_lo_u32 v1, v0, s45
	v_sub_u32_e32 v1, v143, v1
	v_add_u32_e32 v2, 1, v0
	v_cmp_le_u32_e32 vcc, s45, v1
	s_lshl_b32 s24, s10, 5
	s_lshl_b32 s25, s10, 4
	v_cndmask_b32_e32 v0, v0, v2, vcc
	v_subrev_u32_e32 v2, s45, v1
	v_cndmask_b32_e32 v1, v1, v2, vcc
	v_add_u32_e32 v2, 1, v0
	v_cmp_le_u32_e32 vcc, s45, v1
	s_nop 1
	v_cndmask_b32_e32 v0, v0, v2, vcc
	v_mul_lo_u32 v1, v0, s45
	v_sub_u32_e32 v1, v143, v1
	v_lshlrev_b32_e32 v1, 3, v1
	v_add_u32_e32 v2, s35, v1
	v_lshlrev_b32_e32 v68, 2, v2
	v_add_u32_e32 v69, 0x2c00, v68
	global_load_dwordx4 v[4:7], v68, s[6:7] offset:16
	global_load_dwordx4 v[8:11], v68, s[6:7]
	global_load_dwordx4 v[12:15], v69, s[6:7] offset:16
	global_load_dwordx4 v[16:19], v69, s[6:7]
	global_load_dwordx4 v[20:23], v68, s[16:17] offset:16
	global_load_dwordx4 v[24:27], v68, s[16:17]
	global_load_dwordx4 v[28:31], v69, s[16:17] offset:16
	global_load_dwordx4 v[32:35], v69, s[16:17]
	global_load_dwordx4 v[36:39], v68, s[18:19] offset:16
	global_load_dwordx4 v[40:43], v68, s[18:19]
	global_load_dwordx4 v[44:47], v69, s[18:19] offset:16
	global_load_dwordx4 v[48:51], v69, s[18:19]
	global_load_dwordx4 v[52:55], v68, s[8:9] offset:16
	global_load_dwordx4 v[56:59], v68, s[8:9]
	global_load_dwordx4 v[60:63], v69, s[8:9] offset:16
	global_load_dwordx4 v[64:67], v69, s[8:9]
	v_lshlrev_b32_e32 v1, 1, v1
	v_mul_lo_u32 v2, v0, s24
	v_add_u32_e32 v2, v2, v1
	v_mul_lo_u32 v68, v144, s25
	v_add_u32_e32 v2, v2, v68
	v_lshl_add_u64 v[68:69], s[4:5], 0, v[2:3]
	v_mul_lo_u32 v2, v0, s25
	v_add_u32_e32 v2, v2, v1
	s_lshl_b32 s24, s10, 3
	v_mul_lo_u32 v1, v144, s24
	v_add_u32_e32 v2, v2, v1
	v_lshl_add_u64 v[70:71], s[40:41], 0, v[2:3]
	v_lshl_add_u64 v[72:73], s[14:15], 1, v[68:69]
	v_and_b32_e32 v0, 0x7f, v0
	v_or_b32_e32 v1, v0, v144
	v_cmp_ne_u32_e64 s[2:3], 0, v1
	v_lshl_or_b32 v1, v144, 7, v0
	v_mov_b32_e32 v2, 0xff
	v_cmp_ne_u32_e64 s[20:21], v1, v2
	global_load_dwordx4 v[160:163], v[72:73], off nt
	v_lshl_add_u64 v[72:73], v[72:73], 0, s[10:11]
	global_load_dwordx4 v[164:167], v[72:73], off nt
	v_lshl_add_u64 v[72:73], v[72:73], 0, s[10:11]
	global_load_dwordx4 v[168:171], v[72:73], off nt
	v_lshl_add_u64 v[72:73], v[72:73], 0, s[10:11]
	global_load_dwordx4 v[172:175], v[72:73], off nt
	v_lshl_add_u64 v[72:73], v[72:73], 0, s[10:11]
	global_load_dwordx4 v[176:179], v[72:73], off nt
	v_lshl_add_u64 v[72:73], v[72:73], 0, s[10:11]
	global_load_dwordx4 v[180:183], v[72:73], off nt
	v_lshl_add_u64 v[72:73], v[72:73], 0, s[10:11]
	global_load_dwordx4 v[184:187], v[72:73], off nt
	v_lshl_add_u64 v[72:73], v[72:73], 0, s[10:11]
	global_load_dwordx4 v[188:191], v[72:73], off nt
	v_lshl_add_u64 v[72:73], v[72:73], 0, s[10:11]
	global_load_dwordx4 v[192:195], v[72:73], off nt
	v_lshl_add_u64 v[72:73], v[72:73], 0, s[10:11]
	global_load_dwordx4 v[196:199], v[72:73], off nt
	v_lshl_add_u64 v[72:73], v[72:73], 0, s[10:11]
	global_load_dwordx4 v[200:203], v[72:73], off nt
	v_lshl_add_u64 v[72:73], v[72:73], 0, s[10:11]
	global_load_dwordx4 v[204:207], v[72:73], off nt
	v_lshl_add_u64 v[72:73], v[72:73], 0, s[10:11]
	global_load_dwordx4 v[208:211], v[72:73], off nt
	v_lshl_add_u64 v[72:73], v[72:73], 0, s[10:11]
	global_load_dwordx4 v[212:215], v[72:73], off nt
	v_lshl_add_u64 v[72:73], v[72:73], 0, s[10:11]
	global_load_dwordx4 v[216:219], v[72:73], off nt
	v_lshl_add_u64 v[72:73], v[72:73], 0, s[10:11]
	global_load_dwordx4 v[220:223], v[72:73], off nt
	v_lshl_add_u64 v[72:73], v[72:73], 0, s[10:11]
	global_load_dwordx4 v[224:227], v[72:73], off nt
	v_lshl_add_u64 v[72:73], v[72:73], 0, s[10:11]
	global_load_dwordx4 v[228:231], v[72:73], off nt
	v_lshl_add_u64 v[72:73], v[72:73], 0, s[10:11]
	global_load_dwordx4 v[232:235], v[72:73], off nt
	v_lshl_add_u64 v[72:73], v[72:73], 0, s[10:11]
	global_load_dwordx4 v[236:239], v[72:73], off nt
	v_lshl_add_u64 v[72:73], v[72:73], 0, s[10:11]
	s_waitcnt vmcnt(20)
	s_waitcnt vmcnt(18)
	v_cndmask_b32_e64 v160, 0, v160, s[2:3]
	v_cndmask_b32_e64 v161, 0, v161, s[2:3]
	v_cndmask_b32_e64 v162, 0, v162, s[2:3]
	v_cndmask_b32_e64 v163, 0, v163, s[2:3]
	v_cndmask_b32_e64 v164, 0, v164, s[2:3]
	v_cndmask_b32_e64 v165, 0, v165, s[2:3]
	v_cndmask_b32_e64 v166, 0, v166, s[2:3]
	v_cndmask_b32_e64 v167, 0, v167, s[2:3]
	v_lshlrev_b32_e32 v126, 16, v160
	v_and_b32_e32 v127, 0xffff0000, v160
	v_pk_fma_f32 v[74:75], v[8:9], v[126:127], v[56:57]
	v_lshlrev_b32_e32 v128, 16, v161
	v_and_b32_e32 v129, 0xffff0000, v161
	v_pk_fma_f32 v[76:77], v[10:11], v[128:129], v[58:59]
	v_lshlrev_b32_e32 v126, 16, v162
	v_and_b32_e32 v127, 0xffff0000, v162
	v_pk_fma_f32 v[78:79], v[4:5], v[126:127], v[52:53]
	v_lshlrev_b32_e32 v128, 16, v163
	v_and_b32_e32 v129, 0xffff0000, v163
	v_pk_fma_f32 v[80:81], v[6:7], v[128:129], v[54:55]
	v_lshlrev_b32_e32 v126, 16, v164
	v_and_b32_e32 v127, 0xffff0000, v164
	v_pk_fma_f32 v[82:83], v[16:17], v[126:127], v[64:65]
	v_lshlrev_b32_e32 v128, 16, v165
	v_and_b32_e32 v129, 0xffff0000, v165
	v_pk_fma_f32 v[84:85], v[18:19], v[128:129], v[66:67]
	v_lshlrev_b32_e32 v126, 16, v166
	v_and_b32_e32 v127, 0xffff0000, v166
	v_pk_fma_f32 v[86:87], v[12:13], v[126:127], v[60:61]
	v_lshlrev_b32_e32 v128, 16, v167
	v_and_b32_e32 v129, 0xffff0000, v167
	v_pk_fma_f32 v[88:89], v[14:15], v[128:129], v[62:63]
	s_waitcnt vmcnt(16)
; __device__ __forceinline__ uint4 ld_nt16(const void* p) { const u32x4_t t = __builtin_nontemporal_load((const u32x4_t*)p); return make_uint4(t[0], t[1], t[2], t[3]); }
; __device__ __forceinline__ unsigned pk2(float lo, float hi) { f32x2_t v = {lo, hi}; bf16x2_t b = __builtin_convertvector(v, bf16x2_t); return __builtin_bit_cast(unsigned, b); }
; __device__ __forceinline__ float lo_bf(unsigned u) { return __uint_as_float(u << 16); }
; __device__ __forceinline__ float hi_bf(unsigned u) { return __uint_as_float(u & 0xffff0000u); }
; __device__ __forceinline__ float siluf_(float x) { return x * __builtin_amdgcn_rcpf(1.f + __expf(-x)); }
; __device__ void conv_phase(int swave, const Params& p, int layer, int h) {
;     ...
;     for (int i = 0; i < 16; ++i) {
;       uint4 na = zero4, nv = zero4;
;       if (s0 + i + 1 < SEQ) { na = ld_nt16(base + (size_t)(i + 1) * ULD); nv = ld_nt16(base + (size_t)(i + 1) * ULD + FFNH); }
;       const unsigned rp[4] = {pa.x, pa.y, pa.z, pa.w}, rc[4] = {ca.x, ca.y, ca.z, ca.w}, rn[4] = {na.x, na.y, na.z, na.w};
;       const unsigned qp[4] = {pv.x, pv.y, pv.z, pv.w}, qc[4] = {cv.x, cv.y, cv.z, cv.w}, qn[4] = {nv.x, nv.y, nv.z, nv.w};
;       float oa[8], ov[8];
; #pragma unroll
;       for (int e = 0; e < 4; ++e) {
;         oa[2 * e] = ba[2 * e] + lo_bf(rp[e]) * wa[0][2 * e] + lo_bf(rc[e]) * wa[1][2 * e] + lo_bf(rn[e]) * wa[2][2 * e];
;         oa[2 * e + 1] = ba[2 * e + 1] + hi_bf(rp[e]) * wa[0][2 * e + 1] + hi_bf(rc[e]) * wa[1][2 * e + 1] + hi_bf(rn[e]) * wa[2][2 * e + 1];
;         ov[2 * e] = bv[2 * e] + lo_bf(qp[e]) * wv[0][2 * e] + lo_bf(qc[e]) * wv[1][2 * e] + lo_bf(qn[e]) * wv[2][2 * e];
;         ov[2 * e + 1] = bv[2 * e + 1] + hi_bf(qp[e]) * wv[0][2 * e + 1] + hi_bf(qc[e]) * wv[1][2 * e + 1] + hi_bf(qn[e]) * wv[2][2 * e + 1];
;       }
;       uint4 o;
;       o.x = pk2(siluf_(oa[0]) * ov[0], siluf_(oa[1]) * ov[1]); o.y = pk2(siluf_(oa[2]) * ov[2], siluf_(oa[3]) * ov[3]);
;       o.z = pk2(siluf_(oa[4]) * ov[4], siluf_(oa[5]) * ov[5]); o.w = pk2(siluf_(oa[6]) * ov[6], siluf_(oa[7]) * ov[7]);
;       *(uint4*)(ACT + (size_t)(t0 + i) * FFNH + f8) = o;
	v_lshlrev_b32_e32 v126, 16, v168
	v_and_b32_e32 v127, 0xffff0000, v168
	v_pk_fma_f32 v[90:91], v[8:9], v[126:127], v[56:57]
	v_pk_fma_f32 v[74:75], v[24:25], v[126:127], v[74:75]
	v_lshlrev_b32_e32 v128, 16, v169
	v_and_b32_e32 v129, 0xffff0000, v169
	v_pk_fma_f32 v[92:93], v[10:11], v[128:129], v[58:59]
	v_pk_fma_f32 v[76:77], v[26:27], v[128:129], v[76:77]
	v_lshlrev_b32_e32 v126, 16, v170
	v_and_b32_e32 v127, 0xffff0000, v170
	v_pk_fma_f32 v[94:95], v[4:5], v[126:127], v[52:53]
	v_pk_fma_f32 v[78:79], v[20:21], v[126:127], v[78:79]
	v_lshlrev_b32_e32 v128, 16, v171
	v_and_b32_e32 v129, 0xffff0000, v171
	v_pk_fma_f32 v[96:97], v[6:7], v[128:129], v[54:55]
	v_pk_fma_f32 v[80:81], v[22:23], v[128:129], v[80:81]
	v_lshlrev_b32_e32 v126, 16, v172
	v_and_b32_e32 v127, 0xffff0000, v172
	v_pk_fma_f32 v[98:99], v[16:17], v[126:127], v[64:65]
	v_pk_fma_f32 v[82:83], v[32:33], v[126:127], v[82:83]
	v_lshlrev_b32_e32 v128, 16, v173
	v_and_b32_e32 v129, 0xffff0000, v173
	v_pk_fma_f32 v[100:101], v[18:19], v[128:129], v[66:67]
	v_pk_fma_f32 v[84:85], v[34:35], v[128:129], v[84:85]
	v_lshlrev_b32_e32 v126, 16, v174
	v_and_b32_e32 v127, 0xffff0000, v174
	v_pk_fma_f32 v[102:103], v[12:13], v[126:127], v[60:61]
	v_pk_fma_f32 v[86:87], v[28:29], v[126:127], v[86:87]
	v_lshlrev_b32_e32 v128, 16, v175
	v_and_b32_e32 v129, 0xffff0000, v175
	v_pk_fma_f32 v[104:105], v[14:15], v[128:129], v[62:63]
	v_pk_fma_f32 v[88:89], v[30:31], v[128:129], v[88:89]
	s_waitcnt vmcnt(14)
	v_lshlrev_b32_e32 v126, 16, v176
	v_and_b32_e32 v127, 0xffff0000, v176
	v_pk_fma_f32 v[106:107], v[8:9], v[126:127], v[56:57]
	v_pk_fma_f32 v[90:91], v[24:25], v[126:127], v[90:91]
	v_pk_fma_f32 v[74:75], v[40:41], v[126:127], v[74:75]
	v_lshlrev_b32_e32 v128, 16, v177
	v_and_b32_e32 v129, 0xffff0000, v177
	v_pk_fma_f32 v[108:109], v[10:11], v[128:129], v[58:59]
	v_pk_fma_f32 v[92:93], v[26:27], v[128:129], v[92:93]
	v_pk_fma_f32 v[76:77], v[42:43], v[128:129], v[76:77]
	v_lshlrev_b32_e32 v126, 16, v178
	v_and_b32_e32 v127, 0xffff0000, v178
	v_pk_fma_f32 v[110:111], v[4:5], v[126:127], v[52:53]
	v_pk_fma_f32 v[94:95], v[20:21], v[126:127], v[94:95]
	v_pk_fma_f32 v[78:79], v[36:37], v[126:127], v[78:79]
	v_lshlrev_b32_e32 v128, 16, v179
	v_and_b32_e32 v129, 0xffff0000, v179
	v_pk_fma_f32 v[112:113], v[6:7], v[128:129], v[54:55]
	v_pk_fma_f32 v[96:97], v[22:23], v[128:129], v[96:97]
	v_pk_fma_f32 v[80:81], v[38:39], v[128:129], v[80:81]
	v_lshlrev_b32_e32 v126, 16, v180
	v_and_b32_e32 v127, 0xffff0000, v180
	v_pk_fma_f32 v[114:115], v[16:17], v[126:127], v[64:65]
	v_pk_fma_f32 v[98:99], v[32:33], v[126:127], v[98:99]
	v_pk_fma_f32 v[82:83], v[48:49], v[126:127], v[82:83]
	v_lshlrev_b32_e32 v128, 16, v181
	v_and_b32_e32 v129, 0xffff0000, v181
	v_pk_fma_f32 v[116:117], v[18:19], v[128:129], v[66:67]
	v_pk_fma_f32 v[100:101], v[34:35], v[128:129], v[100:101]
	v_pk_fma_f32 v[84:85], v[50:51], v[128:129], v[84:85]
	v_lshlrev_b32_e32 v126, 16, v182
	v_and_b32_e32 v127, 0xffff0000, v182
	v_pk_fma_f32 v[118:119], v[12:13], v[126:127], v[60:61]
	v_pk_fma_f32 v[102:103], v[28:29], v[126:127], v[102:103]
	v_pk_fma_f32 v[86:87], v[44:45], v[126:127], v[86:87]
	v_lshlrev_b32_e32 v128, 16, v183
	v_and_b32_e32 v129, 0xffff0000, v183
	v_pk_fma_f32 v[120:121], v[14:15], v[128:129], v[62:63]
	v_pk_fma_f32 v[104:105], v[30:31], v[128:129], v[104:105]
	v_pk_fma_f32 v[88:89], v[46:47], v[128:129], v[88:89]
	v_mul_f32_e32 v122, 0xbfb8aa3b, v74
	v_mul_f32_e32 v123, 0xbfb8aa3b, v75
	v_mul_f32_e32 v124, 0xbfb8aa3b, v76
	v_mul_f32_e32 v125, 0xbfb8aa3b, v77
	v_mul_f32_e32 v126, 0xbfb8aa3b, v78
	v_mul_f32_e32 v127, 0xbfb8aa3b, v79
	v_mul_f32_e32 v128, 0xbfb8aa3b, v80
	v_mul_f32_e32 v129, 0xbfb8aa3b, v81
	v_exp_f32_e32 v122, v122
	v_exp_f32_e32 v123, v123
	v_exp_f32_e32 v124, v124
	v_exp_f32_e32 v125, v125
	v_exp_f32_e32 v126, v126
	v_exp_f32_e32 v127, v127
	v_exp_f32_e32 v128, v128
	v_exp_f32_e32 v129, v129
	v_add_f32_e32 v122, 1.0, v122
	v_add_f32_e32 v123, 1.0, v123
	v_add_f32_e32 v124, 1.0, v124
	v_add_f32_e32 v125, 1.0, v125
	v_add_f32_e32 v126, 1.0, v126
	v_add_f32_e32 v127, 1.0, v127
	v_add_f32_e32 v128, 1.0, v128
	v_add_f32_e32 v129, 1.0, v129
	v_rcp_f32_e32 v122, v122
	v_rcp_f32_e32 v123, v123
	v_rcp_f32_e32 v124, v124
	v_rcp_f32_e32 v125, v125
	v_rcp_f32_e32 v126, v126
	v_rcp_f32_e32 v127, v127
	v_rcp_f32_e32 v128, v128
	v_rcp_f32_e32 v129, v129
	v_pk_mul_f32 v[74:75], v[74:75], v[122:123]
	v_pk_mul_f32 v[76:77], v[76:77], v[124:125]
	v_pk_mul_f32 v[78:79], v[78:79], v[126:127]
	v_pk_mul_f32 v[80:81], v[80:81], v[128:129]
	v_pk_mul_f32 v[74:75], v[82:83], v[74:75]
	v_pk_mul_f32 v[76:77], v[84:85], v[76:77]
	v_pk_mul_f32 v[78:79], v[86:87], v[78:79]
	v_pk_mul_f32 v[80:81], v[88:89], v[80:81]
	v_cvt_pk_bf16_f32 v138, v74, v75
	v_cvt_pk_bf16_f32 v139, v76, v77
	v_cvt_pk_bf16_f32 v140, v78, v79
	v_cvt_pk_bf16_f32 v141, v80, v81
	global_store_dwordx4 v[70:71], v[138:141], off
	v_lshl_add_u64 v[70:71], v[70:71], 0, s[10:11]
	s_waitcnt vmcnt(13)
; __device__ __forceinline__ uint4 ld_nt16(const void* p) { const u32x4_t t = __builtin_nontemporal_load((const u32x4_t*)p); return make_uint4(t[0], t[1], t[2], t[3]); }
; __device__ __forceinline__ unsigned pk2(float lo, float hi) { f32x2_t v = {lo, hi}; bf16x2_t b = __builtin_convertvector(v, bf16x2_t); return __builtin_bit_cast(unsigned, b); }
; __device__ __forceinline__ float lo_bf(unsigned u) { return __uint_as_float(u << 16); }
; __device__ __forceinline__ float hi_bf(unsigned u) { return __uint_as_float(u & 0xffff0000u); }
; __device__ __forceinline__ float siluf_(float x) { return x * __builtin_amdgcn_rcpf(1.f + __expf(-x)); }
; __device__ void conv_phase(int swave, const Params& p, int layer, int h) {
;     ...
;     for (int i = 0; i < 16; ++i) {
;       uint4 na = zero4, nv = zero4;
;       if (s0 + i + 1 < SEQ) { na = ld_nt16(base + (size_t)(i + 1) * ULD); nv = ld_nt16(base + (size_t)(i + 1) * ULD + FFNH); }
;       const unsigned rp[4] = {pa.x, pa.y, pa.z, pa.w}, rc[4] = {ca.x, ca.y, ca.z, ca.w}, rn[4] = {na.x, na.y, na.z, na.w};
;       const unsigned qp[4] = {pv.x, pv.y, pv.z, pv.w}, qc[4] = {cv.x, cv.y, cv.z, cv.w}, qn[4] = {nv.x, nv.y, nv.z, nv.w};
;       float oa[8], ov[8];
; #pragma unroll
;       for (int e = 0; e < 4; ++e) {
;         oa[2 * e] = ba[2 * e] + lo_bf(rp[e]) * wa[0][2 * e] + lo_bf(rc[e]) * wa[1][2 * e] + lo_bf(rn[e]) * wa[2][2 * e];
;         oa[2 * e + 1] = ba[2 * e + 1] + hi_bf(rp[e]) * wa[0][2 * e + 1] + hi_bf(rc[e]) * wa[1][2 * e + 1] + hi_bf(rn[e]) * wa[2][2 * e + 1];
;         ov[2 * e] = bv[2 * e] + lo_bf(qp[e]) * wv[0][2 * e] + lo_bf(qc[e]) * wv[1][2 * e] + lo_bf(qn[e]) * wv[2][2 * e];
;         ov[2 * e + 1] = bv[2 * e + 1] + hi_bf(qp[e]) * wv[0][2 * e + 1] + hi_bf(qc[e]) * wv[1][2 * e + 1] + hi_bf(qn[e]) * wv[2][2 * e + 1];
;       }
;       uint4 o;
;       o.x = pk2(siluf_(oa[0]) * ov[0], siluf_(oa[1]) * ov[1]); o.y = pk2(siluf_(oa[2]) * ov[2], siluf_(oa[3]) * ov[3]);
;       o.z = pk2(siluf_(oa[4]) * ov[4], siluf_(oa[5]) * ov[5]); o.w = pk2(siluf_(oa[6]) * ov[6], siluf_(oa[7]) * ov[7]);
;       *(uint4*)(ACT + (size_t)(t0 + i) * FFNH + f8) = o;
	v_lshlrev_b32_e32 v126, 16, v184
	v_and_b32_e32 v127, 0xffff0000, v184
	v_pk_fma_f32 v[74:75], v[8:9], v[126:127], v[56:57]
	v_pk_fma_f32 v[106:107], v[24:25], v[126:127], v[106:107]
	v_pk_fma_f32 v[90:91], v[40:41], v[126:127], v[90:91]
	v_lshlrev_b32_e32 v128, 16, v185
	v_and_b32_e32 v129, 0xffff0000, v185
	v_pk_fma_f32 v[76:77], v[10:11], v[128:129], v[58:59]
	v_pk_fma_f32 v[108:109], v[26:27], v[128:129], v[108:109]
	v_pk_fma_f32 v[92:93], v[42:43], v[128:129], v[92:93]
	v_lshlrev_b32_e32 v126, 16, v186
	v_and_b32_e32 v127, 0xffff0000, v186
	v_pk_fma_f32 v[78:79], v[4:5], v[126:127], v[52:53]
	v_pk_fma_f32 v[110:111], v[20:21], v[126:127], v[110:111]
	v_pk_fma_f32 v[94:95], v[36:37], v[126:127], v[94:95]
	v_lshlrev_b32_e32 v128, 16, v187
	v_and_b32_e32 v129, 0xffff0000, v187
	v_pk_fma_f32 v[80:81], v[6:7], v[128:129], v[54:55]
	v_pk_fma_f32 v[112:113], v[22:23], v[128:129], v[112:113]
	v_pk_fma_f32 v[96:97], v[38:39], v[128:129], v[96:97]
	v_lshlrev_b32_e32 v126, 16, v188
	v_and_b32_e32 v127, 0xffff0000, v188
	v_pk_fma_f32 v[82:83], v[16:17], v[126:127], v[64:65]
	v_pk_fma_f32 v[114:115], v[32:33], v[126:127], v[114:115]
	v_pk_fma_f32 v[98:99], v[48:49], v[126:127], v[98:99]
	v_lshlrev_b32_e32 v128, 16, v189
	v_and_b32_e32 v129, 0xffff0000, v189
	v_pk_fma_f32 v[84:85], v[18:19], v[128:129], v[66:67]
	v_pk_fma_f32 v[116:117], v[34:35], v[128:129], v[116:117]
	v_pk_fma_f32 v[100:101], v[50:51], v[128:129], v[100:101]
	v_lshlrev_b32_e32 v126, 16, v190
	v_and_b32_e32 v127, 0xffff0000, v190
	v_pk_fma_f32 v[86:87], v[12:13], v[126:127], v[60:61]
	v_pk_fma_f32 v[118:119], v[28:29], v[126:127], v[118:119]
	v_pk_fma_f32 v[102:103], v[44:45], v[126:127], v[102:103]
	v_lshlrev_b32_e32 v128, 16, v191
	v_and_b32_e32 v129, 0xffff0000, v191
	v_pk_fma_f32 v[88:89], v[14:15], v[128:129], v[62:63]
	v_pk_fma_f32 v[120:121], v[30:31], v[128:129], v[120:121]
	v_pk_fma_f32 v[104:105], v[46:47], v[128:129], v[104:105]
	v_mul_f32_e32 v122, 0xbfb8aa3b, v90
	v_mul_f32_e32 v123, 0xbfb8aa3b, v91
	v_mul_f32_e32 v124, 0xbfb8aa3b, v92
	v_mul_f32_e32 v125, 0xbfb8aa3b, v93
	v_mul_f32_e32 v126, 0xbfb8aa3b, v94
	v_mul_f32_e32 v127, 0xbfb8aa3b, v95
	v_mul_f32_e32 v128, 0xbfb8aa3b, v96
	v_mul_f32_e32 v129, 0xbfb8aa3b, v97
	v_exp_f32_e32 v122, v122
	v_exp_f32_e32 v123, v123
	v_exp_f32_e32 v124, v124
	v_exp_f32_e32 v125, v125
	v_exp_f32_e32 v126, v126
	v_exp_f32_e32 v127, v127
	v_exp_f32_e32 v128, v128
	v_exp_f32_e32 v129, v129
	v_add_f32_e32 v122, 1.0, v122
	v_add_f32_e32 v123, 1.0, v123
	v_add_f32_e32 v124, 1.0, v124
	v_add_f32_e32 v125, 1.0, v125
	v_add_f32_e32 v126, 1.0, v126
	v_add_f32_e32 v127, 1.0, v127
	v_add_f32_e32 v128, 1.0, v128
	v_add_f32_e32 v129, 1.0, v129
	v_rcp_f32_e32 v122, v122
	v_rcp_f32_e32 v123, v123
	v_rcp_f32_e32 v124, v124
	v_rcp_f32_e32 v125, v125
	v_rcp_f32_e32 v126, v126
	v_rcp_f32_e32 v127, v127
	v_rcp_f32_e32 v128, v128
	v_rcp_f32_e32 v129, v129
	v_pk_mul_f32 v[90:91], v[90:91], v[122:123]
	v_pk_mul_f32 v[92:93], v[92:93], v[124:125]
	v_pk_mul_f32 v[94:95], v[94:95], v[126:127]
	v_pk_mul_f32 v[96:97], v[96:97], v[128:129]
	v_pk_mul_f32 v[90:91], v[98:99], v[90:91]
	v_pk_mul_f32 v[92:93], v[100:101], v[92:93]
	v_pk_mul_f32 v[94:95], v[102:103], v[94:95]
	v_pk_mul_f32 v[96:97], v[104:105], v[96:97]
	v_cvt_pk_bf16_f32 v138, v90, v91
	v_cvt_pk_bf16_f32 v139, v92, v93
	v_cvt_pk_bf16_f32 v140, v94, v95
	v_cvt_pk_bf16_f32 v141, v96, v97
	global_store_dwordx4 v[70:71], v[138:141], off
	v_lshl_add_u64 v[70:71], v[70:71], 0, s[10:11]
	s_waitcnt vmcnt(12)
	v_lshlrev_b32_e32 v126, 16, v192
	v_and_b32_e32 v127, 0xffff0000, v192
	v_pk_fma_f32 v[90:91], v[8:9], v[126:127], v[56:57]
	v_pk_fma_f32 v[74:75], v[24:25], v[126:127], v[74:75]
	v_pk_fma_f32 v[106:107], v[40:41], v[126:127], v[106:107]
	v_lshlrev_b32_e32 v128, 16, v193
	v_and_b32_e32 v129, 0xffff0000, v193
	v_pk_fma_f32 v[92:93], v[10:11], v[128:129], v[58:59]
	v_pk_fma_f32 v[76:77], v[26:27], v[128:129], v[76:77]
	v_pk_fma_f32 v[108:109], v[42:43], v[128:129], v[108:109]
	v_lshlrev_b32_e32 v126, 16, v194
	v_and_b32_e32 v127, 0xffff0000, v194
	v_pk_fma_f32 v[94:95], v[4:5], v[126:127], v[52:53]
	v_pk_fma_f32 v[78:79], v[20:21], v[126:127], v[78:79]
	v_pk_fma_f32 v[110:111], v[36:37], v[126:127], v[110:111]
	v_lshlrev_b32_e32 v128, 16, v195
	v_and_b32_e32 v129, 0xffff0000, v195
	v_pk_fma_f32 v[96:97], v[6:7], v[128:129], v[54:55]
	v_pk_fma_f32 v[80:81], v[22:23], v[128:129], v[80:81]
	v_pk_fma_f32 v[112:113], v[38:39], v[128:129], v[112:113]
	v_lshlrev_b32_e32 v126, 16, v196
	v_and_b32_e32 v127, 0xffff0000, v196
	v_pk_fma_f32 v[98:99], v[16:17], v[126:127], v[64:65]
	v_pk_fma_f32 v[82:83], v[32:33], v[126:127], v[82:83]
	v_pk_fma_f32 v[114:115], v[48:49], v[126:127], v[114:115]
	v_lshlrev_b32_e32 v128, 16, v197
	v_and_b32_e32 v129, 0xffff0000, v197
	v_pk_fma_f32 v[100:101], v[18:19], v[128:129], v[66:67]
	v_pk_fma_f32 v[84:85], v[34:35], v[128:129], v[84:85]
	v_pk_fma_f32 v[116:117], v[50:51], v[128:129], v[116:117]
	v_lshlrev_b32_e32 v126, 16, v198
	v_and_b32_e32 v127, 0xffff0000, v198
	v_pk_fma_f32 v[102:103], v[12:13], v[126:127], v[60:61]
	v_pk_fma_f32 v[86:87], v[28:29], v[126:127], v[86:87]
	v_pk_fma_f32 v[118:119], v[44:45], v[126:127], v[118:119]
	v_lshlrev_b32_e32 v128, 16, v199
	v_and_b32_e32 v129, 0xffff0000, v199
	v_pk_fma_f32 v[104:105], v[14:15], v[128:129], v[62:63]
	v_pk_fma_f32 v[88:89], v[30:31], v[128:129], v[88:89]
	v_pk_fma_f32 v[120:121], v[46:47], v[128:129], v[120:121]
	v_mul_f32_e32 v122, 0xbfb8aa3b, v106
	v_mul_f32_e32 v123, 0xbfb8aa3b, v107
	v_mul_f32_e32 v124, 0xbfb8aa3b, v108
	v_mul_f32_e32 v125, 0xbfb8aa3b, v109
	v_mul_f32_e32 v126, 0xbfb8aa3b, v110
; __device__ __forceinline__ uint4 ld_nt16(const void* p) { const u32x4_t t = __builtin_nontemporal_load((const u32x4_t*)p); return make_uint4(t[0], t[1], t[2], t[3]); }
; __device__ __forceinline__ unsigned pk2(float lo, float hi) { f32x2_t v = {lo, hi}; bf16x2_t b = __builtin_convertvector(v, bf16x2_t); return __builtin_bit_cast(unsigned, b); }
; __device__ __forceinline__ float lo_bf(unsigned u) { return __uint_as_float(u << 16); }
; __device__ __forceinline__ float hi_bf(unsigned u) { return __uint_as_float(u & 0xffff0000u); }
; __device__ __forceinline__ float siluf_(float x) { return x * __builtin_amdgcn_rcpf(1.f + __expf(-x)); }
; __device__ void conv_phase(int swave, const Params& p, int layer, int h) {
;     ...
;     for (int i = 0; i < 16; ++i) {
;       uint4 na = zero4, nv = zero4;
;       if (s0 + i + 1 < SEQ) { na = ld_nt16(base + (size_t)(i + 1) * ULD); nv = ld_nt16(base + (size_t)(i + 1) * ULD + FFNH); }
;       const unsigned rp[4] = {pa.x, pa.y, pa.z, pa.w}, rc[4] = {ca.x, ca.y, ca.z, ca.w}, rn[4] = {na.x, na.y, na.z, na.w};
;       const unsigned qp[4] = {pv.x, pv.y, pv.z, pv.w}, qc[4] = {cv.x, cv.y, cv.z, cv.w}, qn[4] = {nv.x, nv.y, nv.z, nv.w};
;       float oa[8], ov[8];
; #pragma unroll
;       for (int e = 0; e < 4; ++e) {
;         oa[2 * e] = ba[2 * e] + lo_bf(rp[e]) * wa[0][2 * e] + lo_bf(rc[e]) * wa[1][2 * e] + lo_bf(rn[e]) * wa[2][2 * e];
;         oa[2 * e + 1] = ba[2 * e + 1] + hi_bf(rp[e]) * wa[0][2 * e + 1] + hi_bf(rc[e]) * wa[1][2 * e + 1] + hi_bf(rn[e]) * wa[2][2 * e + 1];
;         ov[2 * e] = bv[2 * e] + lo_bf(qp[e]) * wv[0][2 * e] + lo_bf(qc[e]) * wv[1][2 * e] + lo_bf(qn[e]) * wv[2][2 * e];
;         ov[2 * e + 1] = bv[2 * e + 1] + hi_bf(qp[e]) * wv[0][2 * e + 1] + hi_bf(qc[e]) * wv[1][2 * e + 1] + hi_bf(qn[e]) * wv[2][2 * e + 1];
;       }
;       uint4 o;
;       o.x = pk2(siluf_(oa[0]) * ov[0], siluf_(oa[1]) * ov[1]); o.y = pk2(siluf_(oa[2]) * ov[2], siluf_(oa[3]) * ov[3]);
;       o.z = pk2(siluf_(oa[4]) * ov[4], siluf_(oa[5]) * ov[5]); o.w = pk2(siluf_(oa[6]) * ov[6], siluf_(oa[7]) * ov[7]);
;       *(uint4*)(ACT + (size_t)(t0 + i) * FFNH + f8) = o;
	v_mul_f32_e32 v127, 0xbfb8aa3b, v111
	v_mul_f32_e32 v128, 0xbfb8aa3b, v112
	v_mul_f32_e32 v129, 0xbfb8aa3b, v113
	v_exp_f32_e32 v122, v122
	v_exp_f32_e32 v123, v123
	v_exp_f32_e32 v124, v124
	v_exp_f32_e32 v125, v125
	v_exp_f32_e32 v126, v126
	v_exp_f32_e32 v127, v127
	v_exp_f32_e32 v128, v128
	v_exp_f32_e32 v129, v129
	v_add_f32_e32 v122, 1.0, v122
	v_add_f32_e32 v123, 1.0, v123
	v_add_f32_e32 v124, 1.0, v124
	v_add_f32_e32 v125, 1.0, v125
	v_add_f32_e32 v126, 1.0, v126
	v_add_f32_e32 v127, 1.0, v127
	v_add_f32_e32 v128, 1.0, v128
	v_add_f32_e32 v129, 1.0, v129
	v_rcp_f32_e32 v122, v122
	v_rcp_f32_e32 v123, v123
	v_rcp_f32_e32 v124, v124
	v_rcp_f32_e32 v125, v125
	v_rcp_f32_e32 v126, v126
	v_rcp_f32_e32 v127, v127
	v_rcp_f32_e32 v128, v128
	v_rcp_f32_e32 v129, v129
	v_pk_mul_f32 v[106:107], v[106:107], v[122:123]
	v_pk_mul_f32 v[108:109], v[108:109], v[124:125]
	v_pk_mul_f32 v[110:111], v[110:111], v[126:127]
	v_pk_mul_f32 v[112:113], v[112:113], v[128:129]
	v_pk_mul_f32 v[106:107], v[114:115], v[106:107]
	v_pk_mul_f32 v[108:109], v[116:117], v[108:109]
	v_pk_mul_f32 v[110:111], v[118:119], v[110:111]
	v_pk_mul_f32 v[112:113], v[120:121], v[112:113]
	v_cvt_pk_bf16_f32 v138, v106, v107
	v_cvt_pk_bf16_f32 v139, v108, v109
	v_cvt_pk_bf16_f32 v140, v110, v111
	v_cvt_pk_bf16_f32 v141, v112, v113
	global_store_dwordx4 v[70:71], v[138:141], off
	v_lshl_add_u64 v[70:71], v[70:71], 0, s[10:11]
	s_waitcnt vmcnt(11)
	v_lshlrev_b32_e32 v126, 16, v200
	v_and_b32_e32 v127, 0xffff0000, v200
	v_pk_fma_f32 v[106:107], v[8:9], v[126:127], v[56:57]
	v_pk_fma_f32 v[90:91], v[24:25], v[126:127], v[90:91]
	v_pk_fma_f32 v[74:75], v[40:41], v[126:127], v[74:75]
	v_lshlrev_b32_e32 v128, 16, v201
	v_and_b32_e32 v129, 0xffff0000, v201
	v_pk_fma_f32 v[108:109], v[10:11], v[128:129], v[58:59]
	v_pk_fma_f32 v[92:93], v[26:27], v[128:129], v[92:93]
	v_pk_fma_f32 v[76:77], v[42:43], v[128:129], v[76:77]
	v_lshlrev_b32_e32 v126, 16, v202
	v_and_b32_e32 v127, 0xffff0000, v202
	v_pk_fma_f32 v[110:111], v[4:5], v[126:127], v[52:53]
	v_pk_fma_f32 v[94:95], v[20:21], v[126:127], v[94:95]
	v_pk_fma_f32 v[78:79], v[36:37], v[126:127], v[78:79]
	v_lshlrev_b32_e32 v128, 16, v203
	v_and_b32_e32 v129, 0xffff0000, v203
	v_pk_fma_f32 v[112:113], v[6:7], v[128:129], v[54:55]
	v_pk_fma_f32 v[96:97], v[22:23], v[128:129], v[96:97]
	v_pk_fma_f32 v[80:81], v[38:39], v[128:129], v[80:81]
	v_lshlrev_b32_e32 v126, 16, v204
	v_and_b32_e32 v127, 0xffff0000, v204
	v_pk_fma_f32 v[114:115], v[16:17], v[126:127], v[64:65]
	v_pk_fma_f32 v[98:99], v[32:33], v[126:127], v[98:99]
	v_pk_fma_f32 v[82:83], v[48:49], v[126:127], v[82:83]
	v_lshlrev_b32_e32 v128, 16, v205
	v_and_b32_e32 v129, 0xffff0000, v205
	v_pk_fma_f32 v[116:117], v[18:19], v[128:129], v[66:67]
	v_pk_fma_f32 v[100:101], v[34:35], v[128:129], v[100:101]
	v_pk_fma_f32 v[84:85], v[50:51], v[128:129], v[84:85]
	v_lshlrev_b32_e32 v126, 16, v206
	v_and_b32_e32 v127, 0xffff0000, v206
	v_pk_fma_f32 v[118:119], v[12:13], v[126:127], v[60:61]
	v_pk_fma_f32 v[102:103], v[28:29], v[126:127], v[102:103]
	v_pk_fma_f32 v[86:87], v[44:45], v[126:127], v[86:87]
	v_lshlrev_b32_e32 v128, 16, v207
	v_and_b32_e32 v129, 0xffff0000, v207
	v_pk_fma_f32 v[120:121], v[14:15], v[128:129], v[62:63]
	v_pk_fma_f32 v[104:105], v[30:31], v[128:129], v[104:105]
	v_pk_fma_f32 v[88:89], v[46:47], v[128:129], v[88:89]
	v_mul_f32_e32 v122, 0xbfb8aa3b, v74
	v_mul_f32_e32 v123, 0xbfb8aa3b, v75
	v_mul_f32_e32 v124, 0xbfb8aa3b, v76
	v_mul_f32_e32 v125, 0xbfb8aa3b, v77
	v_mul_f32_e32 v126, 0xbfb8aa3b, v78
	v_mul_f32_e32 v127, 0xbfb8aa3b, v79
	v_mul_f32_e32 v128, 0xbfb8aa3b, v80
	v_mul_f32_e32 v129, 0xbfb8aa3b, v81
	v_exp_f32_e32 v122, v122
	v_exp_f32_e32 v123, v123
	v_exp_f32_e32 v124, v124
	v_exp_f32_e32 v125, v125
	v_exp_f32_e32 v126, v126
	v_exp_f32_e32 v127, v127
	v_exp_f32_e32 v128, v128
	v_exp_f32_e32 v129, v129
	v_add_f32_e32 v122, 1.0, v122
	v_add_f32_e32 v123, 1.0, v123
	v_add_f32_e32 v124, 1.0, v124
	v_add_f32_e32 v125, 1.0, v125
	v_add_f32_e32 v126, 1.0, v126
	v_add_f32_e32 v127, 1.0, v127
	v_add_f32_e32 v128, 1.0, v128
	v_add_f32_e32 v129, 1.0, v129
	v_rcp_f32_e32 v122, v122
	v_rcp_f32_e32 v123, v123
	v_rcp_f32_e32 v124, v124
	v_rcp_f32_e32 v125, v125
	v_rcp_f32_e32 v126, v126
	v_rcp_f32_e32 v127, v127
	v_rcp_f32_e32 v128, v128
	v_rcp_f32_e32 v129, v129
	v_pk_mul_f32 v[74:75], v[74:75], v[122:123]
	v_pk_mul_f32 v[76:77], v[76:77], v[124:125]
	v_pk_mul_f32 v[78:79], v[78:79], v[126:127]
	v_pk_mul_f32 v[80:81], v[80:81], v[128:129]
	v_pk_mul_f32 v[74:75], v[82:83], v[74:75]
	v_pk_mul_f32 v[76:77], v[84:85], v[76:77]
	v_pk_mul_f32 v[78:79], v[86:87], v[78:79]
	v_pk_mul_f32 v[80:81], v[88:89], v[80:81]
	v_cvt_pk_bf16_f32 v138, v74, v75
	v_cvt_pk_bf16_f32 v139, v76, v77
	v_cvt_pk_bf16_f32 v140, v78, v79
	v_cvt_pk_bf16_f32 v141, v80, v81
	global_store_dwordx4 v[70:71], v[138:141], off
	v_lshl_add_u64 v[70:71], v[70:71], 0, s[10:11]
	s_waitcnt vmcnt(10)
; __device__ __forceinline__ uint4 ld_nt16(const void* p) { const u32x4_t t = __builtin_nontemporal_load((const u32x4_t*)p); return make_uint4(t[0], t[1], t[2], t[3]); }
; __device__ __forceinline__ unsigned pk2(float lo, float hi) { f32x2_t v = {lo, hi}; bf16x2_t b = __builtin_convertvector(v, bf16x2_t); return __builtin_bit_cast(unsigned, b); }
; __device__ __forceinline__ float lo_bf(unsigned u) { return __uint_as_float(u << 16); }
; __device__ __forceinline__ float hi_bf(unsigned u) { return __uint_as_float(u & 0xffff0000u); }
; __device__ __forceinline__ float siluf_(float x) { return x * __builtin_amdgcn_rcpf(1.f + __expf(-x)); }
; __device__ void conv_phase(int swave, const Params& p, int layer, int h) {
;     ...
;     for (int i = 0; i < 16; ++i) {
;       uint4 na = zero4, nv = zero4;
;       if (s0 + i + 1 < SEQ) { na = ld_nt16(base + (size_t)(i + 1) * ULD); nv = ld_nt16(base + (size_t)(i + 1) * ULD + FFNH); }
;       const unsigned rp[4] = {pa.x, pa.y, pa.z, pa.w}, rc[4] = {ca.x, ca.y, ca.z, ca.w}, rn[4] = {na.x, na.y, na.z, na.w};
;       const unsigned qp[4] = {pv.x, pv.y, pv.z, pv.w}, qc[4] = {cv.x, cv.y, cv.z, cv.w}, qn[4] = {nv.x, nv.y, nv.z, nv.w};
;       float oa[8], ov[8];
; #pragma unroll
;       for (int e = 0; e < 4; ++e) {
;         oa[2 * e] = ba[2 * e] + lo_bf(rp[e]) * wa[0][2 * e] + lo_bf(rc[e]) * wa[1][2 * e] + lo_bf(rn[e]) * wa[2][2 * e];
;         oa[2 * e + 1] = ba[2 * e + 1] + hi_bf(rp[e]) * wa[0][2 * e + 1] + hi_bf(rc[e]) * wa[1][2 * e + 1] + hi_bf(rn[e]) * wa[2][2 * e + 1];
;         ov[2 * e] = bv[2 * e] + lo_bf(qp[e]) * wv[0][2 * e] + lo_bf(qc[e]) * wv[1][2 * e] + lo_bf(qn[e]) * wv[2][2 * e];
;         ov[2 * e + 1] = bv[2 * e + 1] + hi_bf(qp[e]) * wv[0][2 * e + 1] + hi_bf(qc[e]) * wv[1][2 * e + 1] + hi_bf(qn[e]) * wv[2][2 * e + 1];
;       }
;       uint4 o;
;       o.x = pk2(siluf_(oa[0]) * ov[0], siluf_(oa[1]) * ov[1]); o.y = pk2(siluf_(oa[2]) * ov[2], siluf_(oa[3]) * ov[3]);
;       o.z = pk2(siluf_(oa[4]) * ov[4], siluf_(oa[5]) * ov[5]); o.w = pk2(siluf_(oa[6]) * ov[6], siluf_(oa[7]) * ov[7]);
;       *(uint4*)(ACT + (size_t)(t0 + i) * FFNH + f8) = o;
	v_lshlrev_b32_e32 v126, 16, v208
	v_and_b32_e32 v127, 0xffff0000, v208
	v_pk_fma_f32 v[74:75], v[8:9], v[126:127], v[56:57]
	v_pk_fma_f32 v[106:107], v[24:25], v[126:127], v[106:107]
	v_pk_fma_f32 v[90:91], v[40:41], v[126:127], v[90:91]
	v_lshlrev_b32_e32 v128, 16, v209
	v_and_b32_e32 v129, 0xffff0000, v209
	v_pk_fma_f32 v[76:77], v[10:11], v[128:129], v[58:59]
	v_pk_fma_f32 v[108:109], v[26:27], v[128:129], v[108:109]
	v_pk_fma_f32 v[92:93], v[42:43], v[128:129], v[92:93]
	v_lshlrev_b32_e32 v126, 16, v210
	v_and_b32_e32 v127, 0xffff0000, v210
	v_pk_fma_f32 v[78:79], v[4:5], v[126:127], v[52:53]
	v_pk_fma_f32 v[110:111], v[20:21], v[126:127], v[110:111]
	v_pk_fma_f32 v[94:95], v[36:37], v[126:127], v[94:95]
	v_lshlrev_b32_e32 v128, 16, v211
	v_and_b32_e32 v129, 0xffff0000, v211
	v_pk_fma_f32 v[80:81], v[6:7], v[128:129], v[54:55]
	v_pk_fma_f32 v[112:113], v[22:23], v[128:129], v[112:113]
	v_pk_fma_f32 v[96:97], v[38:39], v[128:129], v[96:97]
	v_lshlrev_b32_e32 v126, 16, v212
	v_and_b32_e32 v127, 0xffff0000, v212
	v_pk_fma_f32 v[82:83], v[16:17], v[126:127], v[64:65]
	v_pk_fma_f32 v[114:115], v[32:33], v[126:127], v[114:115]
	v_pk_fma_f32 v[98:99], v[48:49], v[126:127], v[98:99]
	v_lshlrev_b32_e32 v128, 16, v213
	v_and_b32_e32 v129, 0xffff0000, v213
	v_pk_fma_f32 v[84:85], v[18:19], v[128:129], v[66:67]
	v_pk_fma_f32 v[116:117], v[34:35], v[128:129], v[116:117]
	v_pk_fma_f32 v[100:101], v[50:51], v[128:129], v[100:101]
	v_lshlrev_b32_e32 v126, 16, v214
	v_and_b32_e32 v127, 0xffff0000, v214
	v_pk_fma_f32 v[86:87], v[12:13], v[126:127], v[60:61]
	v_pk_fma_f32 v[118:119], v[28:29], v[126:127], v[118:119]
	v_pk_fma_f32 v[102:103], v[44:45], v[126:127], v[102:103]
	v_lshlrev_b32_e32 v128, 16, v215
	v_and_b32_e32 v129, 0xffff0000, v215
	v_pk_fma_f32 v[88:89], v[14:15], v[128:129], v[62:63]
	v_pk_fma_f32 v[120:121], v[30:31], v[128:129], v[120:121]
	v_pk_fma_f32 v[104:105], v[46:47], v[128:129], v[104:105]
	v_mul_f32_e32 v122, 0xbfb8aa3b, v90
	v_mul_f32_e32 v123, 0xbfb8aa3b, v91
	v_mul_f32_e32 v124, 0xbfb8aa3b, v92
	v_mul_f32_e32 v125, 0xbfb8aa3b, v93
	v_mul_f32_e32 v126, 0xbfb8aa3b, v94
	v_mul_f32_e32 v127, 0xbfb8aa3b, v95
	v_mul_f32_e32 v128, 0xbfb8aa3b, v96
	v_mul_f32_e32 v129, 0xbfb8aa3b, v97
	v_exp_f32_e32 v122, v122
	v_exp_f32_e32 v123, v123
	v_exp_f32_e32 v124, v124
	v_exp_f32_e32 v125, v125
	v_exp_f32_e32 v126, v126
	v_exp_f32_e32 v127, v127
	v_exp_f32_e32 v128, v128
	v_exp_f32_e32 v129, v129
	v_add_f32_e32 v122, 1.0, v122
	v_add_f32_e32 v123, 1.0, v123
	v_add_f32_e32 v124, 1.0, v124
	v_add_f32_e32 v125, 1.0, v125
	v_add_f32_e32 v126, 1.0, v126
	v_add_f32_e32 v127, 1.0, v127
	v_add_f32_e32 v128, 1.0, v128
	v_add_f32_e32 v129, 1.0, v129
	v_rcp_f32_e32 v122, v122
	v_rcp_f32_e32 v123, v123
	v_rcp_f32_e32 v124, v124
	v_rcp_f32_e32 v125, v125
	v_rcp_f32_e32 v126, v126
	v_rcp_f32_e32 v127, v127
	v_rcp_f32_e32 v128, v128
	v_rcp_f32_e32 v129, v129
	v_pk_mul_f32 v[90:91], v[90:91], v[122:123]
	v_pk_mul_f32 v[92:93], v[92:93], v[124:125]
	v_pk_mul_f32 v[94:95], v[94:95], v[126:127]
	v_pk_mul_f32 v[96:97], v[96:97], v[128:129]
	v_pk_mul_f32 v[90:91], v[98:99], v[90:91]
	v_pk_mul_f32 v[92:93], v[100:101], v[92:93]
	v_pk_mul_f32 v[94:95], v[102:103], v[94:95]
	v_pk_mul_f32 v[96:97], v[104:105], v[96:97]
	v_cvt_pk_bf16_f32 v138, v90, v91
	v_cvt_pk_bf16_f32 v139, v92, v93
	v_cvt_pk_bf16_f32 v140, v94, v95
	v_cvt_pk_bf16_f32 v141, v96, v97
	global_store_dwordx4 v[70:71], v[138:141], off
	v_lshl_add_u64 v[70:71], v[70:71], 0, s[10:11]
	s_waitcnt vmcnt(9)
	v_lshlrev_b32_e32 v126, 16, v216
	v_and_b32_e32 v127, 0xffff0000, v216
	v_pk_fma_f32 v[90:91], v[8:9], v[126:127], v[56:57]
	v_pk_fma_f32 v[74:75], v[24:25], v[126:127], v[74:75]
	v_pk_fma_f32 v[106:107], v[40:41], v[126:127], v[106:107]
	v_lshlrev_b32_e32 v128, 16, v217
	v_and_b32_e32 v129, 0xffff0000, v217
	v_pk_fma_f32 v[92:93], v[10:11], v[128:129], v[58:59]
	v_pk_fma_f32 v[76:77], v[26:27], v[128:129], v[76:77]
	v_pk_fma_f32 v[108:109], v[42:43], v[128:129], v[108:109]
	v_lshlrev_b32_e32 v126, 16, v218
	v_and_b32_e32 v127, 0xffff0000, v218
	v_pk_fma_f32 v[94:95], v[4:5], v[126:127], v[52:53]
	v_pk_fma_f32 v[78:79], v[20:21], v[126:127], v[78:79]
	v_pk_fma_f32 v[110:111], v[36:37], v[126:127], v[110:111]
	v_lshlrev_b32_e32 v128, 16, v219
	v_and_b32_e32 v129, 0xffff0000, v219
	v_pk_fma_f32 v[96:97], v[6:7], v[128:129], v[54:55]
	v_pk_fma_f32 v[80:81], v[22:23], v[128:129], v[80:81]
	v_pk_fma_f32 v[112:113], v[38:39], v[128:129], v[112:113]
	v_lshlrev_b32_e32 v126, 16, v220
	v_and_b32_e32 v127, 0xffff0000, v220
	v_pk_fma_f32 v[98:99], v[16:17], v[126:127], v[64:65]
	v_pk_fma_f32 v[82:83], v[32:33], v[126:127], v[82:83]
	v_pk_fma_f32 v[114:115], v[48:49], v[126:127], v[114:115]
	v_lshlrev_b32_e32 v128, 16, v221
	v_and_b32_e32 v129, 0xffff0000, v221
	v_pk_fma_f32 v[100:101], v[18:19], v[128:129], v[66:67]
	v_pk_fma_f32 v[84:85], v[34:35], v[128:129], v[84:85]
	v_pk_fma_f32 v[116:117], v[50:51], v[128:129], v[116:117]
	v_lshlrev_b32_e32 v126, 16, v222
	v_and_b32_e32 v127, 0xffff0000, v222
	v_pk_fma_f32 v[102:103], v[12:13], v[126:127], v[60:61]
	v_pk_fma_f32 v[86:87], v[28:29], v[126:127], v[86:87]
	v_pk_fma_f32 v[118:119], v[44:45], v[126:127], v[118:119]
	v_lshlrev_b32_e32 v128, 16, v223
	v_and_b32_e32 v129, 0xffff0000, v223
	v_pk_fma_f32 v[104:105], v[14:15], v[128:129], v[62:63]
	v_pk_fma_f32 v[88:89], v[30:31], v[128:129], v[88:89]
	v_pk_fma_f32 v[120:121], v[46:47], v[128:129], v[120:121]
	v_mul_f32_e32 v122, 0xbfb8aa3b, v106
	v_mul_f32_e32 v123, 0xbfb8aa3b, v107
	v_mul_f32_e32 v124, 0xbfb8aa3b, v108
	v_mul_f32_e32 v125, 0xbfb8aa3b, v109
	v_mul_f32_e32 v126, 0xbfb8aa3b, v110
; __device__ __forceinline__ uint4 ld_nt16(const void* p) { const u32x4_t t = __builtin_nontemporal_load((const u32x4_t*)p); return make_uint4(t[0], t[1], t[2], t[3]); }
; __device__ __forceinline__ unsigned pk2(float lo, float hi) { f32x2_t v = {lo, hi}; bf16x2_t b = __builtin_convertvector(v, bf16x2_t); return __builtin_bit_cast(unsigned, b); }
; __device__ __forceinline__ float lo_bf(unsigned u) { return __uint_as_float(u << 16); }
; __device__ __forceinline__ float hi_bf(unsigned u) { return __uint_as_float(u & 0xffff0000u); }
; __device__ __forceinline__ float siluf_(float x) { return x * __builtin_amdgcn_rcpf(1.f + __expf(-x)); }
; __device__ void conv_phase(int swave, const Params& p, int layer, int h) {
;     ...
;     for (int i = 0; i < 16; ++i) {
;       uint4 na = zero4, nv = zero4;
;       if (s0 + i + 1 < SEQ) { na = ld_nt16(base + (size_t)(i + 1) * ULD); nv = ld_nt16(base + (size_t)(i + 1) * ULD + FFNH); }
;       const unsigned rp[4] = {pa.x, pa.y, pa.z, pa.w}, rc[4] = {ca.x, ca.y, ca.z, ca.w}, rn[4] = {na.x, na.y, na.z, na.w};
;       const unsigned qp[4] = {pv.x, pv.y, pv.z, pv.w}, qc[4] = {cv.x, cv.y, cv.z, cv.w}, qn[4] = {nv.x, nv.y, nv.z, nv.w};
;       float oa[8], ov[8];
; #pragma unroll
;       for (int e = 0; e < 4; ++e) {
;         oa[2 * e] = ba[2 * e] + lo_bf(rp[e]) * wa[0][2 * e] + lo_bf(rc[e]) * wa[1][2 * e] + lo_bf(rn[e]) * wa[2][2 * e];
;         oa[2 * e + 1] = ba[2 * e + 1] + hi_bf(rp[e]) * wa[0][2 * e + 1] + hi_bf(rc[e]) * wa[1][2 * e + 1] + hi_bf(rn[e]) * wa[2][2 * e + 1];
;         ov[2 * e] = bv[2 * e] + lo_bf(qp[e]) * wv[0][2 * e] + lo_bf(qc[e]) * wv[1][2 * e] + lo_bf(qn[e]) * wv[2][2 * e];
;         ov[2 * e + 1] = bv[2 * e + 1] + hi_bf(qp[e]) * wv[0][2 * e + 1] + hi_bf(qc[e]) * wv[1][2 * e + 1] + hi_bf(qn[e]) * wv[2][2 * e + 1];
;       }
;       uint4 o;
;       o.x = pk2(siluf_(oa[0]) * ov[0], siluf_(oa[1]) * ov[1]); o.y = pk2(siluf_(oa[2]) * ov[2], siluf_(oa[3]) * ov[3]);
;       o.z = pk2(siluf_(oa[4]) * ov[4], siluf_(oa[5]) * ov[5]); o.w = pk2(siluf_(oa[6]) * ov[6], siluf_(oa[7]) * ov[7]);
;       *(uint4*)(ACT + (size_t)(t0 + i) * FFNH + f8) = o;
	v_mul_f32_e32 v127, 0xbfb8aa3b, v111
	v_mul_f32_e32 v128, 0xbfb8aa3b, v112
	v_mul_f32_e32 v129, 0xbfb8aa3b, v113
	v_exp_f32_e32 v122, v122
	v_exp_f32_e32 v123, v123
	v_exp_f32_e32 v124, v124
	v_exp_f32_e32 v125, v125
	v_exp_f32_e32 v126, v126
	v_exp_f32_e32 v127, v127
	v_exp_f32_e32 v128, v128
	v_exp_f32_e32 v129, v129
	v_add_f32_e32 v122, 1.0, v122
	v_add_f32_e32 v123, 1.0, v123
	v_add_f32_e32 v124, 1.0, v124
	v_add_f32_e32 v125, 1.0, v125
	v_add_f32_e32 v126, 1.0, v126
	v_add_f32_e32 v127, 1.0, v127
	v_add_f32_e32 v128, 1.0, v128
	v_add_f32_e32 v129, 1.0, v129
	v_rcp_f32_e32 v122, v122
	v_rcp_f32_e32 v123, v123
	v_rcp_f32_e32 v124, v124
	v_rcp_f32_e32 v125, v125
	v_rcp_f32_e32 v126, v126
	v_rcp_f32_e32 v127, v127
	v_rcp_f32_e32 v128, v128
	v_rcp_f32_e32 v129, v129
	v_pk_mul_f32 v[106:107], v[106:107], v[122:123]
	v_pk_mul_f32 v[108:109], v[108:109], v[124:125]
	v_pk_mul_f32 v[110:111], v[110:111], v[126:127]
	v_pk_mul_f32 v[112:113], v[112:113], v[128:129]
	v_pk_mul_f32 v[106:107], v[114:115], v[106:107]
	v_pk_mul_f32 v[108:109], v[116:117], v[108:109]
	v_pk_mul_f32 v[110:111], v[118:119], v[110:111]
	v_pk_mul_f32 v[112:113], v[120:121], v[112:113]
	v_cvt_pk_bf16_f32 v138, v106, v107
	v_cvt_pk_bf16_f32 v139, v108, v109
	v_cvt_pk_bf16_f32 v140, v110, v111
	v_cvt_pk_bf16_f32 v141, v112, v113
	global_store_dwordx4 v[70:71], v[138:141], off
	v_lshl_add_u64 v[70:71], v[70:71], 0, s[10:11]
	s_waitcnt vmcnt(8)
	v_lshlrev_b32_e32 v126, 16, v224
	v_and_b32_e32 v127, 0xffff0000, v224
	v_pk_fma_f32 v[90:91], v[24:25], v[126:127], v[90:91]
	v_pk_fma_f32 v[74:75], v[40:41], v[126:127], v[74:75]
	v_lshlrev_b32_e32 v128, 16, v225
	v_and_b32_e32 v129, 0xffff0000, v225
	v_pk_fma_f32 v[92:93], v[26:27], v[128:129], v[92:93]
	v_pk_fma_f32 v[76:77], v[42:43], v[128:129], v[76:77]
	v_lshlrev_b32_e32 v126, 16, v226
	v_and_b32_e32 v127, 0xffff0000, v226
	v_pk_fma_f32 v[94:95], v[20:21], v[126:127], v[94:95]
	v_pk_fma_f32 v[78:79], v[36:37], v[126:127], v[78:79]
	v_lshlrev_b32_e32 v128, 16, v227
	v_and_b32_e32 v129, 0xffff0000, v227
	v_pk_fma_f32 v[96:97], v[22:23], v[128:129], v[96:97]
	v_pk_fma_f32 v[80:81], v[38:39], v[128:129], v[80:81]
	v_lshlrev_b32_e32 v126, 16, v228
	v_and_b32_e32 v127, 0xffff0000, v228
	v_pk_fma_f32 v[98:99], v[32:33], v[126:127], v[98:99]
	v_pk_fma_f32 v[82:83], v[48:49], v[126:127], v[82:83]
	v_lshlrev_b32_e32 v128, 16, v229
	v_and_b32_e32 v129, 0xffff0000, v229
	v_pk_fma_f32 v[100:101], v[34:35], v[128:129], v[100:101]
	v_pk_fma_f32 v[84:85], v[50:51], v[128:129], v[84:85]
	v_lshlrev_b32_e32 v126, 16, v230
	v_and_b32_e32 v127, 0xffff0000, v230
	v_pk_fma_f32 v[102:103], v[28:29], v[126:127], v[102:103]
	v_pk_fma_f32 v[86:87], v[44:45], v[126:127], v[86:87]
	v_lshlrev_b32_e32 v128, 16, v231
	v_and_b32_e32 v129, 0xffff0000, v231
	v_pk_fma_f32 v[104:105], v[30:31], v[128:129], v[104:105]
	v_pk_fma_f32 v[88:89], v[46:47], v[128:129], v[88:89]
	v_mul_f32_e32 v122, 0xbfb8aa3b, v74
	v_mul_f32_e32 v123, 0xbfb8aa3b, v75
	v_mul_f32_e32 v124, 0xbfb8aa3b, v76
	v_mul_f32_e32 v125, 0xbfb8aa3b, v77
	v_mul_f32_e32 v126, 0xbfb8aa3b, v78
	v_mul_f32_e32 v127, 0xbfb8aa3b, v79
	v_mul_f32_e32 v128, 0xbfb8aa3b, v80
	v_mul_f32_e32 v129, 0xbfb8aa3b, v81
	v_exp_f32_e32 v122, v122
	v_exp_f32_e32 v123, v123
	v_exp_f32_e32 v124, v124
	v_exp_f32_e32 v125, v125
	v_exp_f32_e32 v126, v126
	v_exp_f32_e32 v127, v127
	v_exp_f32_e32 v128, v128
	v_exp_f32_e32 v129, v129
	v_add_f32_e32 v122, 1.0, v122
	v_add_f32_e32 v123, 1.0, v123
	v_add_f32_e32 v124, 1.0, v124
	v_add_f32_e32 v125, 1.0, v125
	v_add_f32_e32 v126, 1.0, v126
	v_add_f32_e32 v127, 1.0, v127
	v_add_f32_e32 v128, 1.0, v128
	v_add_f32_e32 v129, 1.0, v129
	v_rcp_f32_e32 v122, v122
	v_rcp_f32_e32 v123, v123
	v_rcp_f32_e32 v124, v124
	v_rcp_f32_e32 v125, v125
	v_rcp_f32_e32 v126, v126
	v_rcp_f32_e32 v127, v127
	v_rcp_f32_e32 v128, v128
	v_rcp_f32_e32 v129, v129
	v_pk_mul_f32 v[74:75], v[74:75], v[122:123]
	v_pk_mul_f32 v[76:77], v[76:77], v[124:125]
	v_pk_mul_f32 v[78:79], v[78:79], v[126:127]
	v_pk_mul_f32 v[80:81], v[80:81], v[128:129]
	v_pk_mul_f32 v[74:75], v[82:83], v[74:75]
	v_pk_mul_f32 v[76:77], v[84:85], v[76:77]
	v_pk_mul_f32 v[78:79], v[86:87], v[78:79]
	v_pk_mul_f32 v[80:81], v[88:89], v[80:81]
	v_cvt_pk_bf16_f32 v138, v74, v75
	v_cvt_pk_bf16_f32 v139, v76, v77
	v_cvt_pk_bf16_f32 v140, v78, v79
	v_cvt_pk_bf16_f32 v141, v80, v81
	global_store_dwordx4 v[70:71], v[138:141], off
	v_lshl_add_u64 v[70:71], v[70:71], 0, s[10:11]
	s_waitcnt vmcnt(7)
; __device__ __forceinline__ uint4 ld_nt16(const void* p) { const u32x4_t t = __builtin_nontemporal_load((const u32x4_t*)p); return make_uint4(t[0], t[1], t[2], t[3]); }
; __device__ __forceinline__ unsigned pk2(float lo, float hi) { f32x2_t v = {lo, hi}; bf16x2_t b = __builtin_convertvector(v, bf16x2_t); return __builtin_bit_cast(unsigned, b); }
; __device__ __forceinline__ float lo_bf(unsigned u) { return __uint_as_float(u << 16); }
; __device__ __forceinline__ float hi_bf(unsigned u) { return __uint_as_float(u & 0xffff0000u); }
; __device__ __forceinline__ float siluf_(float x) { return x * __builtin_amdgcn_rcpf(1.f + __expf(-x)); }
; __device__ void conv_phase(int swave, const Params& p, int layer, int h) {
;     ...
;     if (s0 > 0) { pa = ld_nt16(base - ULD); pv = ld_nt16(base - ULD + FFNH); }
;     uint4 ca = ld_nt16(base), cv = ld_nt16(base + FFNH);
; #pragma unroll 4
;     for (int i = 0; i < 16; ++i) {
;       uint4 na = zero4, nv = zero4;
;       if (s0 + i + 1 < SEQ) { na = ld_nt16(base + (size_t)(i + 1) * ULD); nv = ld_nt16(base + (size_t)(i + 1) * ULD + FFNH); }
;       const unsigned rp[4] = {pa.x, pa.y, pa.z, pa.w}, rc[4] = {ca.x, ca.y, ca.z, ca.w}, rn[4] = {na.x, na.y, na.z, na.w};
;       const unsigned qp[4] = {pv.x, pv.y, pv.z, pv.w}, qc[4] = {cv.x, cv.y, cv.z, cv.w}, qn[4] = {nv.x, nv.y, nv.z, nv.w};
;       float oa[8], ov[8];
; #pragma unroll
;       for (int e = 0; e < 4; ++e) {
;         oa[2 * e] = ba[2 * e] + lo_bf(rp[e]) * wa[0][2 * e] + lo_bf(rc[e]) * wa[1][2 * e] + lo_bf(rn[e]) * wa[2][2 * e];
;         oa[2 * e + 1] = ba[2 * e + 1] + hi_bf(rp[e]) * wa[0][2 * e + 1] + hi_bf(rc[e]) * wa[1][2 * e + 1] + hi_bf(rn[e]) * wa[2][2 * e + 1];
;         ov[2 * e] = bv[2 * e] + lo_bf(qp[e]) * wv[0][2 * e] + lo_bf(qc[e]) * wv[1][2 * e] + lo_bf(qn[e]) * wv[2][2 * e];
;         ov[2 * e + 1] = bv[2 * e + 1] + hi_bf(qp[e]) * wv[0][2 * e + 1] + hi_bf(qc[e]) * wv[1][2 * e + 1] + hi_bf(qn[e]) * wv[2][2 * e + 1];
;       }
;       uint4 o;
;       o.x = pk2(siluf_(oa[0]) * ov[0], siluf_(oa[1]) * ov[1]); o.y = pk2(siluf_(oa[2]) * ov[2], siluf_(oa[3]) * ov[3]);
;       o.z = pk2(siluf_(oa[4]) * ov[4], siluf_(oa[5]) * ov[5]); o.w = pk2(siluf_(oa[6]) * ov[6], siluf_(oa[7]) * ov[7]);
;       *(uint4*)(ACT + (size_t)(t0 + i) * FFNH + f8) = o;
	v_cndmask_b32_e64 v232, 0, v232, s[20:21]
	v_cndmask_b32_e64 v233, 0, v233, s[20:21]
	v_cndmask_b32_e64 v234, 0, v234, s[20:21]
	v_cndmask_b32_e64 v235, 0, v235, s[20:21]
	v_cndmask_b32_e64 v236, 0, v236, s[20:21]
	v_cndmask_b32_e64 v237, 0, v237, s[20:21]
	v_cndmask_b32_e64 v238, 0, v238, s[20:21]
	v_cndmask_b32_e64 v239, 0, v239, s[20:21]
	v_lshlrev_b32_e32 v126, 16, v232
	v_and_b32_e32 v127, 0xffff0000, v232
	v_pk_fma_f32 v[90:91], v[40:41], v[126:127], v[90:91]
	v_lshlrev_b32_e32 v128, 16, v233
	v_and_b32_e32 v129, 0xffff0000, v233
	v_pk_fma_f32 v[92:93], v[42:43], v[128:129], v[92:93]
	v_lshlrev_b32_e32 v126, 16, v234
	v_and_b32_e32 v127, 0xffff0000, v234
	v_pk_fma_f32 v[94:95], v[36:37], v[126:127], v[94:95]
	v_lshlrev_b32_e32 v128, 16, v235
	v_and_b32_e32 v129, 0xffff0000, v235
	v_pk_fma_f32 v[96:97], v[38:39], v[128:129], v[96:97]
	v_lshlrev_b32_e32 v126, 16, v236
	v_and_b32_e32 v127, 0xffff0000, v236
	v_pk_fma_f32 v[98:99], v[48:49], v[126:127], v[98:99]
	v_lshlrev_b32_e32 v128, 16, v237
	v_and_b32_e32 v129, 0xffff0000, v237
	v_pk_fma_f32 v[100:101], v[50:51], v[128:129], v[100:101]
	v_lshlrev_b32_e32 v126, 16, v238
	v_and_b32_e32 v127, 0xffff0000, v238
	v_pk_fma_f32 v[102:103], v[44:45], v[126:127], v[102:103]
	v_lshlrev_b32_e32 v128, 16, v239
	v_and_b32_e32 v129, 0xffff0000, v239
	v_pk_fma_f32 v[104:105], v[46:47], v[128:129], v[104:105]
	v_mul_f32_e32 v122, 0xbfb8aa3b, v90
	v_mul_f32_e32 v123, 0xbfb8aa3b, v91
	v_mul_f32_e32 v124, 0xbfb8aa3b, v92
	v_mul_f32_e32 v125, 0xbfb8aa3b, v93
	v_mul_f32_e32 v126, 0xbfb8aa3b, v94
	v_mul_f32_e32 v127, 0xbfb8aa3b, v95
	v_mul_f32_e32 v128, 0xbfb8aa3b, v96
	v_mul_f32_e32 v129, 0xbfb8aa3b, v97
	v_exp_f32_e32 v122, v122
	v_exp_f32_e32 v123, v123
	v_exp_f32_e32 v124, v124
	v_exp_f32_e32 v125, v125
	v_exp_f32_e32 v126, v126
	v_exp_f32_e32 v127, v127
	v_exp_f32_e32 v128, v128
	v_exp_f32_e32 v129, v129
	v_add_f32_e32 v122, 1.0, v122
	v_add_f32_e32 v123, 1.0, v123
	v_add_f32_e32 v124, 1.0, v124
	v_add_f32_e32 v125, 1.0, v125
	v_add_f32_e32 v126, 1.0, v126
	v_add_f32_e32 v127, 1.0, v127
	v_add_f32_e32 v128, 1.0, v128
	v_add_f32_e32 v129, 1.0, v129
	v_rcp_f32_e32 v122, v122
	v_rcp_f32_e32 v123, v123
	v_rcp_f32_e32 v124, v124
	v_rcp_f32_e32 v125, v125
	v_rcp_f32_e32 v126, v126
	v_rcp_f32_e32 v127, v127
	v_rcp_f32_e32 v128, v128
	v_rcp_f32_e32 v129, v129
	v_pk_mul_f32 v[90:91], v[90:91], v[122:123]
	v_pk_mul_f32 v[92:93], v[92:93], v[124:125]
	v_pk_mul_f32 v[94:95], v[94:95], v[126:127]
	v_pk_mul_f32 v[96:97], v[96:97], v[128:129]
	v_pk_mul_f32 v[90:91], v[98:99], v[90:91]
	v_pk_mul_f32 v[92:93], v[100:101], v[92:93]
	v_pk_mul_f32 v[94:95], v[102:103], v[94:95]
	v_pk_mul_f32 v[96:97], v[104:105], v[96:97]
	v_cvt_pk_bf16_f32 v138, v90, v91
	v_cvt_pk_bf16_f32 v139, v92, v93
	v_cvt_pk_bf16_f32 v140, v94, v95
	v_cvt_pk_bf16_f32 v141, v96, v97
	global_store_dwordx4 v[70:71], v[138:141], off
	v_lshl_add_u64 v[70:71], v[70:71], 0, s[10:11]
	s_branch .LBB0_715
